# attention loop-edge edits: constant alpha compare branch replaced by s_branch, loop-carried moves rotated above the loop-back barrier, body-2 row-max chain interleaved into the last PV MFMAs (recomput
# baseline (speedup 1.0000x reference)
; __device__ __forceinline__ void finishSM(f32x16& p0, f32x16& p1, float alpha, float& l_reg, bf16x8& pa0, bf16x8& pa1, bf16x8& pa2, bf16x8& pa3) {
; #pragma unroll
;   for (int r = 0; r < 16; ++r) p1[r] = __builtin_amdgcn_exp2f(p1[r]);
;   float ps = 0;
; #pragma unroll
;   for (int r = 0; r < 16; ++r) ps += p0[r];
; #pragma unroll
;   for (int r = 0; r < 16; ++r) ps += p1[r];
;   { auto rr = __builtin_amdgcn_permlane32_swap(__float_as_uint(ps), __float_as_uint(ps), false, false);
; __device__ __forceinline__ void qkt(f32x16& p0, f32x16& p1, const char* Kn, const char* Kr, const char* Qr, const bf16x8* qr, const f32x16& negm, int lane) {
;   const int kn = (int)(uintptr_t)Kn + (lane & 31) * 16 + (lane >> 5) * 1024, kr = (int)(uintptr_t)Kr + (lane & 31) * 16 + (lane >> 5) * 1024, qa = (int)(uintptr_t)Qr + lane * 16;
;   bf16x8 a0, a1, b0, b1, qa_, qb_;
;     ...
;   a0 = dsr128<0 * 2048>(kn); a1 = dsr128<0 * 2048 + 512>(kn);
;   b0 = dsr128<1 * 2048>(kn); b1 = dsr128<1 * 2048 + 512>(kn); LGKM_W2(2, a0, a1);
;   p0 = __builtin_amdgcn_mfma_f32_32x32x16_bf16(a0, qr[0], negm, 0, 0, 0); p1 = __builtin_amdgcn_mfma_f32_32x32x16_bf16(a1, qr[0], negm, 0, 0, 0);
;   a0 = dsr128<2 * 2048>(kn); a1 = dsr128<2 * 2048 + 512>(kn); LGKM_W2(2, b0, b1); MM(b0, b1, qr[1]);
;   b0 = dsr128<3 * 2048>(kn); b1 = dsr128<3 * 2048 + 512>(kn); LGKM_W2(2, a0, a1); MM(a0, a1, qr[2]);
;   a0 = dsr128<4 * 2048>(kn); a1 = dsr128<4 * 2048 + 512>(kn); LGKM_W2(2, b0, b1); MM(b0, b1, qr[3]);
;   b0 = dsr128<5 * 2048>(kn); b1 = dsr128<5 * 2048 + 512>(kn); LGKM_W2(2, a0, a1); MM(a0, a1, qr[4]);
;   a0 = dsr128<6 * 2048>(kn); a1 = dsr128<6 * 2048 + 512>(kn); LGKM_W2(2, b0, b1); MM(b0, b1, qr[5]);
;   b0 = dsr128<7 * 2048>(kn); b1 = dsr128<7 * 2048 + 512>(kn); LGKM_W2(2, a0, a1); MM(a0, a1, qr[6]);
;   a0 = dsr128<0 * 2048>(kr); a1 = dsr128<0 * 2048 + 512>(kr); qa_ = dsr128<0 * 1024>(qa); LGKM_W2(3, b0, b1); MM(b0, b1, qr[7]);
;   b0 = dsr128<1 * 2048>(kr); b1 = dsr128<1 * 2048 + 512>(kr); qb_ = dsr128<1 * 1024>(qa); LGKM_W3(3, a0, a1, qa_); MM(a0, a1, qa_);
;   a0 = dsr128<2 * 2048>(kr); a1 = dsr128<2 * 2048 + 512>(kr); qa_ = dsr128<2 * 1024>(qa); LGKM_W3(3, b0, b1, qb_); MM(b0, b1, qb_);
;   b0 = dsr128<3 * 2048>(kr); b1 = dsr128<3 * 2048 + 512>(kr); qb_ = dsr128<3 * 1024>(qa); LGKM_W3(3, a0, a1, qa_); MM(a0, a1, qa_);
;   LGKM_W3(0, b0, b1, qb_); MM(b0, b1, qb_);
.LBB0_558:
	ds_read_b128 v[98:101], v204 offset:0
	ds_read_b128 v[178:181], v204 offset:0x200
	ds_read_b128 v[210:213], v204 offset:0x800
	ds_read_b128 v[214:217], v204 offset:0xa00
	v_exp_f32_e32 v82, v82
	s_waitcnt lgkmcnt(2)
	v_exp_f32_e32 v83, v83
	v_mfma_f32_32x32x16_bf16 v[114:129], v[98:101], v[130:133], v[66:81]
	v_exp_f32_e32 v84, v84
	v_exp_f32_e32 v85, v85
	v_exp_f32_e32 v86, v86
	v_exp_f32_e32 v87, v87
	v_exp_f32_e32 v88, v88
	v_exp_f32_e32 v89, v89
	v_mfma_f32_32x32x16_bf16 v[98:113], v[178:181], v[130:133], v[66:81]
	v_exp_f32_e32 v90, v90
	v_add_f32_e32 v251, 0, v172
	v_add_f32_e32 v251, v175, v251
	ds_read_b128 v[178:181], v204 offset:0x1000
	ds_read_b128 v[218:221], v204 offset:0x1200
	s_waitcnt lgkmcnt(2)
	s_nop 0
	v_mfma_f32_32x32x16_bf16 v[114:129], v[210:213], v[134:137], v[114:129]
	v_add_f32_e32 v251, v173, v251
	v_exp_f32_e32 v91, v91
	v_add_f32_e32 v251, v176, v251
	ds_read_b128 v[210:213], v204 offset:0x1800
	v_mfma_f32_32x32x16_bf16 v[98:113], v[214:217], v[134:137], v[98:113]
	v_add_f32_e32 v251, v174, v251
	v_add_f32_e32 v251, v177, v251
	v_exp_f32_e32 v92, v92
	ds_read_b128 v[214:217], v204 offset:0x1a00
	s_waitcnt lgkmcnt(2)
	s_nop 0
	v_mfma_f32_32x32x16_bf16 v[114:129], v[178:181], v[138:141], v[114:129]
	v_add_f32_e32 v251, v170, v251
	v_add_f32_e32 v251, v171, v251
	v_add_f32_e32 v251, v166, v251
	ds_read_b128 v[178:181], v204 offset:0x2000
	v_mfma_f32_32x32x16_bf16 v[98:113], v[218:221], v[138:141], v[98:113]
	v_exp_f32_e32 v93, v93
	v_add_f32_e32 v251, v168, v251
	v_add_f32_e32 v251, v167, v251
	ds_read_b128 v[218:221], v204 offset:0x2200
	s_waitcnt lgkmcnt(2)
	s_nop 0
	v_mfma_f32_32x32x16_bf16 v[114:129], v[210:213], v[142:145], v[114:129]
	v_add_f32_e32 v251, v169, v251
	v_exp_f32_e32 v94, v94
	v_add_f32_e32 v251, v162, v251
	ds_read_b128 v[210:213], v204 offset:0x2800
	v_mfma_f32_32x32x16_bf16 v[98:113], v[214:217], v[142:145], v[98:113]
	v_add_f32_e32 v251, v164, v251
	v_add_f32_e32 v251, v163, v251
	v_exp_f32_e32 v95, v95
	ds_read_b128 v[214:217], v204 offset:0x2a00
	s_waitcnt lgkmcnt(2)
	s_nop 0
	v_mfma_f32_32x32x16_bf16 v[114:129], v[178:181], v[146:149], v[114:129]
	v_add_f32_e32 v251, v165, v251
	v_add_f32_e32 v251, v82, v251
	v_add_f32_e32 v251, v83, v251
	ds_read_b128 v[178:181], v204 offset:0x3000
	v_mfma_f32_32x32x16_bf16 v[98:113], v[218:221], v[146:149], v[98:113]
	v_exp_f32_e32 v96, v96
	v_add_f32_e32 v251, v84, v251
	v_add_f32_e32 v251, v85, v251
	ds_read_b128 v[218:221], v204 offset:0x3200
	s_waitcnt lgkmcnt(2)
	s_nop 0
	v_mfma_f32_32x32x16_bf16 v[114:129], v[210:213], v[150:153], v[114:129]
	v_add_f32_e32 v251, v86, v251
	v_exp_f32_e32 v97, v97
	v_add_f32_e32 v251, v87, v251
	ds_read_b128 v[210:213], v204 offset:0x3800
	v_mfma_f32_32x32x16_bf16 v[98:113], v[214:217], v[150:153], v[98:113]
	v_add_f32_e32 v251, v88, v251
	v_add_f32_e32 v251, v89, v251
	v_add_f32_e32 v251, v90, v251
	v_add_f32_e32 v251, v91, v251
	ds_read_b128 v[214:217], v204 offset:0x3a00
	s_waitcnt lgkmcnt(2)
	s_nop 0
	v_mfma_f32_32x32x16_bf16 v[114:129], v[178:181], v[154:157], v[114:129]
	v_add_f32_e32 v251, v92, v251
	v_add_f32_e32 v251, v93, v251
	v_add_f32_e32 v251, v94, v251
	v_add_f32_e32 v251, v95, v251
	ds_read_b128 v[178:181], v205 offset:0
	v_mfma_f32_32x32x16_bf16 v[98:113], v[218:221], v[154:157], v[98:113]
	v_add_f32_e32 v251, v96, v251
	v_add_f32_e32 v251, v97, v251
	ds_read_b128 v[218:221], v205 offset:0x200
	ds_read_b128 v[222:225], v189 offset:0
	s_waitcnt lgkmcnt(3)
	s_nop 0
	v_mfma_f32_32x32x16_bf16 v[114:129], v[210:213], v[158:161], v[114:129]
	ds_read_b128 v[210:213], v205 offset:0x800
	v_mfma_f32_32x32x16_bf16 v[98:113], v[214:217], v[158:161], v[98:113]
	ds_read_b128 v[214:217], v205 offset:0xa00
	ds_read_b128 v[226:229], v189 offset:0x400
	s_waitcnt lgkmcnt(3)
	s_nop 0
	v_mfma_f32_32x32x16_bf16 v[114:129], v[178:181], v[222:225], v[114:129]
	ds_read_b128 v[178:181], v205 offset:0x1000
	v_mfma_f32_32x32x16_bf16 v[98:113], v[218:221], v[222:225], v[98:113]
	ds_read_b128 v[218:221], v205 offset:0x1200
	ds_read_b128 v[222:225], v189 offset:0x800
	s_waitcnt lgkmcnt(3)
	s_nop 0
	v_mfma_f32_32x32x16_bf16 v[114:129], v[210:213], v[226:229], v[114:129]
	ds_read_b128 v[210:213], v205 offset:0x1800
	v_mfma_f32_32x32x16_bf16 v[98:113], v[214:217], v[226:229], v[98:113]
	ds_read_b128 v[214:217], v205 offset:0x1a00
	ds_read_b128 v[226:229], v189 offset:0xc00
	s_waitcnt lgkmcnt(3)
	s_nop 0
	s_waitcnt lgkmcnt(0)
; #define PV_WAIT(n, f) asm volatile("s_waitcnt lgkmcnt(" #n ")" : "+v"(f.l0), "+v"(f.h0), "+v"(f.l1), "+v"(f.h1), "+v"(f.l2), "+v"(f.h2), "+v"(f.l3), "+v"(f.h3) :: "memory")
; template <bool START>
; __device__ __forceinline__ void partialSM(f32x16& p0, f32x16& p1, float& mhat, f32x16& negm, float& alpha) {
;   float pmax = p0[0];
; #pragma unroll
;   for (int r = 1; r < 16; ++r) pmax = fmaxf(pmax, p0[r]);
; #pragma unroll
;   for (int r = 0; r < 16; ++r) pmax = fmaxf(pmax, p1[r]);
;   { auto rr = __builtin_amdgcn_permlane32_swap(__float_as_uint(pmax), __float_as_uint(pmax), false, false);
;     pmax = fmaxf(__uint_as_float(rr[0]), __uint_as_float(rr[1])); }
;   alpha = 1.f;
;   if (START || __builtin_expect(__any(pmax > THRL), 0)) {
; __device__ __forceinline__ void pv_d0(f32x16* o, int vb, bf16x8 pa0, bf16x8 pa1, bf16x8 pa2, bf16x8 pa3) {
;   VF fa, fb;
;   pv_rd<0>(fa, vb);
;   pv_rd<1>(fb, vb); PV_WAIT(8, fa); pv_mm(o[0], fa, pa0, pa1, pa2, pa3);
;   pv_rd<2>(fa, vb); PV_WAIT(8, fb); pv_mm(o[1], fb, pa0, pa1, pa2, pa3);
;   pv_rd<3>(fb, vb); PV_WAIT(8, fa); pv_mm(o[2], fa, pa0, pa1, pa2, pa3);
;   PV_WAIT(0, fb); pv_mm(o[3], fb, pa0, pa1, pa2, pa3);
; }
	v_mfma_f32_32x32x16_bf16 v[114:129], v[178:181], v[222:225], v[114:129]
	v_cvt_pk_bf16_f32 v178, v90, v91
	v_cvt_pk_bf16_f32 v179, v92, v93
	v_cvt_pk_bf16_f32 v180, v94, v95
	v_cvt_pk_bf16_f32 v181, v96, v97
	v_cvt_pk_bf16_f32 v90, v172, v175
	v_cvt_pk_bf16_f32 v91, v173, v176
	v_cvt_pk_bf16_f32 v92, v174, v177
	v_mfma_f32_32x32x16_bf16 v[98:113], v[218:221], v[222:225], v[98:113]
	v_cvt_pk_bf16_f32 v93, v170, v171
	v_cvt_pk_bf16_f32 v94, v166, v168
	v_cvt_pk_bf16_f32 v95, v167, v169
	v_cvt_pk_bf16_f32 v96, v162, v164
	v_cvt_pk_bf16_f32 v97, v163, v165
	v_cvt_pk_bf16_f32 v174, v82, v83
	v_cvt_pk_bf16_f32 v175, v84, v85
	v_mfma_f32_32x32x16_bf16 v[114:129], v[210:213], v[226:229], v[114:129]
	v_cvt_pk_bf16_f32 v176, v86, v87
	v_cvt_pk_bf16_f32 v177, v88, v89
	v_mov_b32_e32 v210, v251
	v_mov_b32_e32 v211, v251
	s_nop 1
	v_permlane32_swap_b32_e32 v210, v211
	v_permlane32_swap_b32_e32 v90, v92
	v_mfma_f32_32x32x16_bf16 v[98:113], v[214:217], v[226:229], v[98:113]
	v_permlane32_swap_b32_e32 v91, v93
	v_permlane32_swap_b32_e32 v94, v96
	v_permlane32_swap_b32_e32 v95, v97
	v_permlane32_swap_b32_e32 v174, v176
	v_permlane32_swap_b32_e32 v175, v177
	v_permlane32_swap_b32_e32 v178, v180
	v_permlane32_swap_b32_e32 v179, v181
	s_sub_i32 s0, s76, 64
	s_ashr_i32 s1, s0, 31
	s_lshl_b64 s[84:85], s[0:1], 10
	v_lshl_add_u64 v[82:83], v[192:193], 0, s[84:85]
	s_add_i32 s84, s76, 0xffffff80
	s_ashr_i32 s85, s84, 31
	s_lshl_b64 vcc, s[0:1], 7
	s_lshl_b64 s[84:85], s[84:85], 10
	s_add_u32 s84, s33, s84
	s_addc_u32 s85, s82, s85
	global_load_dwordx4 v[162:165], v[82:83], off
	global_load_dwordx4 v[166:169], v[82:83], off offset:128
	v_lshl_add_u64 v[82:83], v[190:191], 0, vcc
	v_lshl_add_u64 v[86:87], v[0:1], 1, s[84:85]
	global_load_dwordx4 v[170:173], v[82:83], off
	s_nop 0
	global_load_dwordx4 v[82:85], v[86:87], off
	v_add_co_u32_e32 v86, vcc, s81, v86
	s_nop 1
	v_addc_co_u32_e32 v87, vcc, 0, v87, vcc
	global_load_dwordx4 v[86:89], v[86:87], off
	ds_read_b64_tr_b16 v[212:213], v202 offset:0
	ds_read_b64_tr_b16 v[214:215], v202 offset:0x800
	ds_read_b64_tr_b16 v[216:217], v202 offset:0x1000
	ds_read_b64_tr_b16 v[218:219], v202 offset:0x1800
	ds_read_b64_tr_b16 v[220:221], v202 offset:0x2000
	ds_read_b64_tr_b16 v[222:223], v202 offset:0x2800
	ds_read_b64_tr_b16 v[224:225], v202 offset:0x3000
	ds_read_b64_tr_b16 v[226:227], v202 offset:0x3800
	ds_read_b64_tr_b16 v[228:229], v202 offset:0x200
	ds_read_b64_tr_b16 v[230:231], v202 offset:0xa00
	ds_read_b64_tr_b16 v[232:233], v202 offset:0x1200
	ds_read_b64_tr_b16 v[234:235], v202 offset:0x1a00
	ds_read_b64_tr_b16 v[236:237], v202 offset:0x2200
	ds_read_b64_tr_b16 v[238:239], v202 offset:0x2a00
	ds_read_b64_tr_b16 v[240:241], v202 offset:0x3200
	ds_read_b64_tr_b16 v[242:243], v202 offset:0x3a00
	s_nop 0
	s_waitcnt lgkmcnt(8)
	s_nop 0
	v_mfma_f32_32x32x16_bf16 v[18:33], v[90:93], v[212:215], v[18:33]
	ds_read_b64_tr_b16 v[212:213], v202 offset:0x400
	ds_read_b64_tr_b16 v[214:215], v202 offset:0xc00
	v_mfma_f32_32x32x16_bf16 v[18:33], v[94:97], v[216:219], v[18:33]
	ds_read_b64_tr_b16 v[216:217], v202 offset:0x1400
	ds_read_b64_tr_b16 v[218:219], v202 offset:0x1c00
	v_mfma_f32_32x32x16_bf16 v[18:33], v[174:177], v[220:223], v[18:33]
	ds_read_b64_tr_b16 v[220:221], v202 offset:0x2400
	ds_read_b64_tr_b16 v[222:223], v202 offset:0x2c00
	v_mfma_f32_32x32x16_bf16 v[18:33], v[178:181], v[224:227], v[18:33]
	ds_read_b64_tr_b16 v[224:225], v202 offset:0x3400
	ds_read_b64_tr_b16 v[226:227], v202 offset:0x3c00
	s_waitcnt lgkmcnt(8)
	s_nop 0
	v_mfma_f32_32x32x16_bf16 v[50:65], v[90:93], v[228:231], v[50:65]
	ds_read_b64_tr_b16 v[228:229], v202 offset:0x600
	ds_read_b64_tr_b16 v[230:231], v202 offset:0xe00
	v_mfma_f32_32x32x16_bf16 v[50:65], v[94:97], v[232:235], v[50:65]
	ds_read_b64_tr_b16 v[232:233], v202 offset:0x1600
	ds_read_b64_tr_b16 v[234:235], v202 offset:0x1e00
	v_mfma_f32_32x32x16_bf16 v[50:65], v[174:177], v[236:239], v[50:65]
	ds_read_b64_tr_b16 v[236:237], v202 offset:0x2600
	ds_read_b64_tr_b16 v[238:239], v202 offset:0x2e00
	v_mfma_f32_32x32x16_bf16 v[50:65], v[178:181], v[240:243], v[50:65]
	ds_read_b64_tr_b16 v[240:241], v202 offset:0x3600
	ds_read_b64_tr_b16 v[242:243], v202 offset:0x3e00
	s_waitcnt lgkmcnt(8)
	s_nop 0
	s_waitcnt lgkmcnt(0)
	v_mfma_f32_32x32x16_bf16 v[34:49], v[90:93], v[212:215], v[34:49]
	v_mfma_f32_32x32x16_bf16 v[2:17], v[90:93], v[228:231], v[2:17]
	v_max_f32_e32 v90, v115, v115
	v_max_f32_e32 v91, v114, v114
	v_max_f32_e32 v90, v91, v90
	v_max3_f32 v90, v90, v116, v117
	v_max3_f32 v90, v90, v118, v119
	v_max3_f32 v90, v90, v120, v121
	v_max3_f32 v90, v90, v122, v123
	v_mfma_f32_32x32x16_bf16 v[34:49], v[94:97], v[216:219], v[34:49]
	v_max3_f32 v90, v90, v124, v125
	v_max3_f32 v90, v90, v126, v127
	v_max3_f32 v90, v90, v128, v129
	v_max3_f32 v90, v90, v98, v99
	v_max3_f32 v90, v90, v100, v101
	v_max3_f32 v90, v90, v102, v103
	v_max3_f32 v90, v90, v104, v105
	v_mfma_f32_32x32x16_bf16 v[2:17], v[94:97], v[232:235], v[2:17]
	v_max3_f32 v90, v90, v106, v107
	v_max3_f32 v90, v90, v108, v109
	v_max3_f32 v90, v90, v110, v111
	v_max3_f32 v90, v90, v112, v113
	v_mov_b32_e32 v91, v90
	s_nop 1
	v_permlane32_swap_b32_e32 v90, v91
	v_mfma_f32_32x32x16_bf16 v[34:49], v[174:177], v[220:223], v[34:49]
	v_max_f32_e32 v91, v91, v91
	v_max_f32_e32 v90, v90, v90
	v_max_f32_e32 v90, v90, v91
	v_cmp_lt_f32_e32 vcc, s89, v90
	v_mfma_f32_32x32x16_bf16 v[2:17], v[174:177], v[236:239], v[2:17]
	v_mfma_f32_32x32x16_bf16 v[34:49], v[178:181], v[224:227], v[34:49]
	v_mfma_f32_32x32x16_bf16 v[2:17], v[178:181], v[240:243], v[2:17]
	s_cbranch_vccnz .LBB0_576
	v_mov_b32_e32 v212, 1.0
	s_branch .LBB0_563

; __device__ __forceinline__ int crow(int r, int hi) { return (r & 3) + 8 * (r >> 2) + 4 * hi; }
; #define RESC(a) do { if (__any((a) < 1.f)) { if (hi == 0) al_l[r32] = (a); asm volatile("s_waitcnt lgkmcnt(0)" ::: "memory"); \
;     _Pragma("unroll") for (int d = 0; d < 4; ++d) _Pragma("unroll") for (int r = 0; r < 16; ++r) o[d][r] *= al_l[crow(r, hi)]; } } while (0)
; template <bool START>
; __device__ __forceinline__ void partialSM(f32x16& p0, f32x16& p1, float& mhat, f32x16& negm, float& alpha) {
;   float pmax = p0[0];
; #pragma unroll
;   for (int r = 1; r < 16; ++r) pmax = fmaxf(pmax, p0[r]);
; #pragma unroll
;   for (int r = 0; r < 16; ++r) pmax = fmaxf(pmax, p1[r]);
;   { auto rr = __builtin_amdgcn_permlane32_swap(__float_as_uint(pmax), __float_as_uint(pmax), false, false);
;     pmax = fmaxf(__uint_as_float(rr[0]), __uint_as_float(rr[1])); }
;   alpha = 1.f;
;   if (START || __builtin_expect(__any(pmax > THRL), 0)) {
; __device__ __forceinline__ void kmask(f32x16& p0, f32x16& p1, int nv, int hi) {
; #pragma unroll
;   for (int r = 0; r < 16; ++r) { const int k = crow(r, hi); if (k >= nv) p0[r] = -1e30f; if (k + 32 >= nv) p1[r] = -1e30f; }
; }
; __device__ __forceinline__ void attn_unit(const bf16* __restrict__ Qg, const bf16* __restrict__ KNg, const bf16* __restrict__ KRg, const bf16* __restrict__ Vg, bf16* __restrict__ AO, ...
;     ...
;     pv_d0(o, vb0 + SHM_V, pa0, pa1, pa2, pa3);
;     if (tbeg + j + 1 == NTt - 1) kmask(pA0, pA1, nv_last, hi);
;     partialSM<false>(pA0, pA1, mhat, negm, alA);
;     RESC(alA);
.LBB0_565:
	s_lshl_b64 s[84:85], vcc, 1
	s_add_u32 s84, s33, s84
	s_addc_u32 s85, s82, s85
	v_lshl_add_u64 v[98:99], v[0:1], 1, s[84:85]
	v_add_co_u32_e32 v102, vcc, s81, v98
	s_nop 1
	v_addc_co_u32_e32 v103, vcc, 0, v99, vcc
	global_load_dwordx4 v[98:101], v[98:99], off
	s_nop 0
	global_load_dwordx4 v[102:105], v[102:103], off
	ds_read_b64_tr_b16 v[216:217], v207 offset:0
	ds_read_b64_tr_b16 v[218:219], v207 offset:0x800
	ds_read_b64_tr_b16 v[220:221], v207 offset:0x1000
	ds_read_b64_tr_b16 v[222:223], v207 offset:0x1800
	ds_read_b64_tr_b16 v[224:225], v207 offset:0x2000
	ds_read_b64_tr_b16 v[226:227], v207 offset:0x2800
	ds_read_b64_tr_b16 v[228:229], v207 offset:0x3000
	ds_read_b64_tr_b16 v[230:231], v207 offset:0x3800
	ds_read_b64_tr_b16 v[232:233], v207 offset:0x200
	ds_read_b64_tr_b16 v[234:235], v207 offset:0xa00
	ds_read_b64_tr_b16 v[236:237], v207 offset:0x1200
	ds_read_b64_tr_b16 v[238:239], v207 offset:0x1a00
	ds_read_b64_tr_b16 v[240:241], v207 offset:0x2200
	ds_read_b64_tr_b16 v[242:243], v207 offset:0x2a00
	ds_read_b64_tr_b16 v[244:245], v207 offset:0x3200
	ds_read_b64_tr_b16 v[246:247], v207 offset:0x3a00
	s_nop 0
	s_waitcnt lgkmcnt(8)
	s_cmp_lg_u32 s75, s83
	v_mfma_f32_32x32x16_bf16 v[18:33], v[106:109], v[216:219], v[18:33]
	ds_read_b64_tr_b16 v[216:217], v207 offset:0x400
	ds_read_b64_tr_b16 v[218:219], v207 offset:0xc00
	v_mfma_f32_32x32x16_bf16 v[18:33], v[110:113], v[220:223], v[18:33]
	ds_read_b64_tr_b16 v[220:221], v207 offset:0x1400
	ds_read_b64_tr_b16 v[222:223], v207 offset:0x1c00
	v_mfma_f32_32x32x16_bf16 v[18:33], v[174:177], v[224:227], v[18:33]
	ds_read_b64_tr_b16 v[224:225], v207 offset:0x2400
	ds_read_b64_tr_b16 v[226:227], v207 offset:0x2c00
	v_mfma_f32_32x32x16_bf16 v[18:33], v[178:181], v[228:231], v[18:33]
	ds_read_b64_tr_b16 v[228:229], v207 offset:0x3400
	ds_read_b64_tr_b16 v[230:231], v207 offset:0x3c00
	s_waitcnt lgkmcnt(8)
	s_nop 0
	v_mfma_f32_32x32x16_bf16 v[50:65], v[106:109], v[232:235], v[50:65]
	ds_read_b64_tr_b16 v[232:233], v207 offset:0x600
	ds_read_b64_tr_b16 v[234:235], v207 offset:0xe00
	v_mfma_f32_32x32x16_bf16 v[50:65], v[110:113], v[236:239], v[50:65]
	ds_read_b64_tr_b16 v[236:237], v207 offset:0x1600
	ds_read_b64_tr_b16 v[238:239], v207 offset:0x1e00
	v_mfma_f32_32x32x16_bf16 v[50:65], v[174:177], v[240:243], v[50:65]
	ds_read_b64_tr_b16 v[240:241], v207 offset:0x2600
	ds_read_b64_tr_b16 v[242:243], v207 offset:0x2e00
	v_mfma_f32_32x32x16_bf16 v[50:65], v[178:181], v[244:247], v[50:65]
	ds_read_b64_tr_b16 v[244:245], v207 offset:0x3600
	ds_read_b64_tr_b16 v[246:247], v207 offset:0x3e00
	s_waitcnt lgkmcnt(8)
	s_nop 0
	s_waitcnt lgkmcnt(0)
	v_mfma_f32_32x32x16_bf16 v[34:49], v[106:109], v[216:219], v[34:49]
	v_mfma_f32_32x32x16_bf16 v[2:17], v[106:109], v[232:235], v[2:17]
	v_max_f32_e32 v106, v115, v115
	v_max_f32_e32 v107, v114, v114
	v_max_f32_e32 v106, v107, v106
	v_max3_f32 v106, v106, v116, v117
	v_max3_f32 v106, v106, v118, v119
	v_mfma_f32_32x32x16_bf16 v[34:49], v[110:113], v[220:223], v[34:49]
	v_max3_f32 v106, v106, v120, v121
	v_max3_f32 v106, v106, v122, v123
	v_max3_f32 v106, v106, v124, v125
	v_max3_f32 v106, v106, v126, v127
	v_max3_f32 v106, v106, v128, v129
	v_mfma_f32_32x32x16_bf16 v[2:17], v[110:113], v[236:239], v[2:17]
	v_max3_f32 v106, v106, v82, v83
	v_max3_f32 v106, v106, v84, v85
	v_max3_f32 v106, v106, v86, v87
	v_max3_f32 v106, v106, v88, v89
	v_max3_f32 v106, v106, v90, v91
	v_mfma_f32_32x32x16_bf16 v[34:49], v[174:177], v[224:227], v[34:49]
	v_max3_f32 v106, v106, v92, v93
	v_max3_f32 v106, v106, v94, v95
	v_max3_f32 v106, v106, v96, v97
	v_mfma_f32_32x32x16_bf16 v[2:17], v[174:177], v[240:243], v[2:17]
	v_mov_b32_e32 v107, v106
	s_nop 1
	v_permlane32_swap_b32_e32 v106, v107
	v_mfma_f32_32x32x16_bf16 v[34:49], v[178:181], v[228:231], v[34:49]
	v_max_f32_e32 v107, v107, v107
	v_max_f32_e32 v106, v106, v106
	v_max_f32_e32 v107, v106, v107
	v_cmp_lt_f32_e32 vcc, s89, v107
	v_mov_b32_e32 v106, 1.0
	v_mfma_f32_32x32x16_bf16 v[2:17], v[178:181], v[244:247], v[2:17]
	s_cbranch_scc1 .LBB0_567
	v_cndmask_b32_e64 v129, v194, v129, s[4:5]
	v_cndmask_b32_e64 v128, v194, v128, s[8:9]
	v_cndmask_b32_e64 v127, v194, v127, s[10:11]
	v_cndmask_b32_e64 v126, v194, v126, s[12:13]
	v_cndmask_b32_e64 v125, v194, v125, s[14:15]
	v_cndmask_b32_e64 v124, v194, v124, s[16:17]
	v_cndmask_b32_e64 v123, v194, v123, s[18:19]
	v_cndmask_b32_e64 v122, v194, v122, s[20:21]
	v_cndmask_b32_e64 v121, v194, v121, s[22:23]
	v_cndmask_b32_e64 v120, v194, v120, s[24:25]
	v_cndmask_b32_e64 v119, v194, v119, s[26:27]
	v_cndmask_b32_e64 v118, v194, v118, s[28:29]
	v_cndmask_b32_e64 v117, v194, v117, s[30:31]
	v_cndmask_b32_e64 v116, v194, v116, s[34:35]
	v_cndmask_b32_e64 v115, v194, v115, s[36:37]
	v_cndmask_b32_e64 v114, v194, v114, s[38:39]
	v_cndmask_b32_e64 v97, v194, v97, s[6:7]
	v_cndmask_b32_e64 v96, v194, v96, s[40:41]
	v_cndmask_b32_e64 v95, v194, v95, s[42:43]
	v_cndmask_b32_e64 v94, v194, v94, s[44:45]
	v_cndmask_b32_e64 v93, v194, v93, s[46:47]
	v_cndmask_b32_e64 v92, v194, v92, s[48:49]
	v_cndmask_b32_e64 v91, v194, v91, s[50:51]
	v_cndmask_b32_e64 v90, v194, v90, s[52:53]
	v_cndmask_b32_e64 v89, v194, v89, s[54:55]
	v_cndmask_b32_e64 v88, v194, v88, s[56:57]
	v_cndmask_b32_e64 v87, v194, v87, s[58:59]
	v_cndmask_b32_e64 v86, v194, v86, s[60:61]
	v_cndmask_b32_e64 v85, v194, v85, s[62:63]
	v_cndmask_b32_e64 v84, v194, v84, s[64:65]
	v_cndmask_b32_e64 v83, v194, v83, s[66:67]
	v_cndmask_b32_e64 v82, v194, v82, s[68:69]
	v_max_f32_e32 v106, v115, v115
	v_max_f32_e32 v107, v114, v114
	v_max_f32_e32 v106, v107, v106
	v_max3_f32 v106, v106, v116, v117
	v_max3_f32 v106, v106, v118, v119
	v_max3_f32 v106, v106, v120, v121
	v_max3_f32 v106, v106, v122, v123
	v_max3_f32 v106, v106, v124, v125
	v_max3_f32 v106, v106, v126, v127
	v_max3_f32 v106, v106, v128, v129
	v_max3_f32 v106, v106, v82, v83
	v_max3_f32 v106, v106, v84, v85
	v_max3_f32 v106, v106, v86, v87
	v_max3_f32 v106, v106, v88, v89
	v_max3_f32 v106, v106, v90, v91
	v_max3_f32 v106, v106, v92, v93
	v_max3_f32 v106, v106, v94, v95
	v_max3_f32 v106, v106, v96, v97
	v_mov_b32_e32 v107, v106
	s_nop 1
	v_permlane32_swap_b32_e32 v106, v107
	v_max_f32_e32 v107, v107, v107
	v_max_f32_e32 v106, v106, v106
	v_max_f32_e32 v107, v106, v107
	v_cmp_lt_f32_e32 vcc, s89, v107
	v_mov_b32_e32 v106, 1.0
.LBB0_567:
	s_cbranch_vccnz .LBB0_577
	s_branch .LBB0_572

; #define KWRITE(b) do { *(bf16x8*)(KN_lds + (b) * SHM_KN + kwoff) = ks0; *(bf16x8*)(KN_lds + (b) * SHM_KN + 8192 + kwoff) = ks1; *(bf16x8*)(KR_lds + (b) * SHM_KR + kwoff) = kr0; } while (0)
; #define VWRITE(b) do { *(bf16x8*)(V_lds + (b) * SHM_V + vst0) = vs0; *(bf16x8*)(V_lds + (b) * SHM_V + vst1) = vs1; } while (0)
; #define SWAIT() asm volatile("s_waitcnt vmcnt(0)" ::: "memory")
; template <bool START>
; __device__ __forceinline__ void partialSM(f32x16& p0, f32x16& p1, float& mhat, f32x16& negm, float& alpha) {
;     ...
;   for (int r = 0; r < 16; ++r) p0[r] = __builtin_amdgcn_exp2f(p0[r]);
; }
; __device__ __forceinline__ void finishSM(f32x16& p0, f32x16& p1, float alpha, float& l_reg, bf16x8& pa0, bf16x8& pa1, bf16x8& pa2, bf16x8& pa3) {
; #pragma unroll
;   for (int r = 0; r < 16; ++r) p1[r] = __builtin_amdgcn_exp2f(p1[r]);
;   float ps = 0;
; #pragma unroll
;   for (int r = 0; r < 16; ++r) ps += p0[r];
; #pragma unroll
;   for (int r = 0; r < 16; ++r) ps += p1[r];
;   { auto rr = __builtin_amdgcn_permlane32_swap(__float_as_uint(ps), __float_as_uint(ps), false, false);
;     ps = __uint_as_float(rr[0]) + __uint_as_float(rr[1]); }
;   l_reg = l_reg * alpha + ps;
; __device__ __forceinline__ void attn_unit(const bf16* __restrict__ Qg, const bf16* __restrict__ KNg, const bf16* __restrict__ KRg, const bf16* __restrict__ Vg, bf16* __restrict__ AO, ...
;     ...
;     SWAIT(); if (more) KWRITE(1); VWRITE(0); __syncthreads();
;   }
.LBB0_574:
	s_waitcnt vmcnt(0)
	ds_write_b128 v198, v[98:101]
	ds_write_b128 v199, v[102:105]
	v_exp_f32_e32 v172, v114
	v_exp_f32_e32 v175, v115
	v_exp_f32_e32 v173, v116
	v_exp_f32_e32 v176, v117
	v_exp_f32_e32 v174, v118
	v_exp_f32_e32 v177, v119
	v_exp_f32_e32 v170, v120
	v_exp_f32_e32 v171, v121
	v_exp_f32_e32 v166, v122
	v_exp_f32_e32 v168, v123
	v_exp_f32_e32 v167, v124
	v_exp_f32_e32 v169, v125
	v_exp_f32_e32 v162, v126
	v_exp_f32_e32 v164, v127
	v_exp_f32_e32 v163, v128
	v_exp_f32_e32 v165, v129
	v_add_f32_e32 v107, v210, v211
	v_fmac_f32_e32 v107, v209, v208
	v_add_f32_e32 v208, v213, v214
	s_add_i32 s0, s83, 2
	s_addk_i32 s76, 0x80
	v_fmac_f32_e32 v208, v107, v212
	s_cmp_ge_u32 s83, s74
	s_mov_b32 s83, s0
	v_mov_b32_e32 v209, v106
	s_waitcnt lgkmcnt(0)
	s_barrier
	s_cbranch_scc0 .LBB0_558
	s_branch .LBB0_578

; __device__ __forceinline__ void finishSM(f32x16& p0, f32x16& p1, float alpha, float& l_reg, bf16x8& pa0, bf16x8& pa1, bf16x8& pa2, bf16x8& pa3) {
; #pragma unroll
;   for (int r = 0; r < 16; ++r) p1[r] = __builtin_amdgcn_exp2f(p1[r]);
;   float ps = 0;
; #pragma unroll
;   for (int r = 0; r < 16; ++r) ps += p0[r];
; #pragma unroll
;   for (int r = 0; r < 16; ++r) ps += p1[r];
;   { auto rr = __builtin_amdgcn_permlane32_swap(__float_as_uint(ps), __float_as_uint(ps), false, false);
; __device__ __forceinline__ void qkt(f32x16& p0, f32x16& p1, const char* Kn, const char* Kr, const char* Qr, const bf16x8* qr, const f32x16& negm, int lane) {
;   const int kn = (int)(uintptr_t)Kn + (lane & 31) * 16 + (lane >> 5) * 1024, kr = (int)(uintptr_t)Kr + (lane & 31) * 16 + (lane >> 5) * 1024, qa = (int)(uintptr_t)Qr + lane * 16;
;   bf16x8 a0, a1, b0, b1, qa_, qb_;
;     ...
;   a0 = dsr128<0 * 2048>(kn); a1 = dsr128<0 * 2048 + 512>(kn);
;   b0 = dsr128<1 * 2048>(kn); b1 = dsr128<1 * 2048 + 512>(kn); LGKM_W2(2, a0, a1);
;   p0 = __builtin_amdgcn_mfma_f32_32x32x16_bf16(a0, qr[0], negm, 0, 0, 0); p1 = __builtin_amdgcn_mfma_f32_32x32x16_bf16(a1, qr[0], negm, 0, 0, 0);
;   a0 = dsr128<2 * 2048>(kn); a1 = dsr128<2 * 2048 + 512>(kn); LGKM_W2(2, b0, b1); MM(b0, b1, qr[1]);
;   b0 = dsr128<3 * 2048>(kn); b1 = dsr128<3 * 2048 + 512>(kn); LGKM_W2(2, a0, a1); MM(a0, a1, qr[2]);
;   a0 = dsr128<4 * 2048>(kn); a1 = dsr128<4 * 2048 + 512>(kn); LGKM_W2(2, b0, b1); MM(b0, b1, qr[3]);
;   b0 = dsr128<5 * 2048>(kn); b1 = dsr128<5 * 2048 + 512>(kn); LGKM_W2(2, a0, a1); MM(a0, a1, qr[4]);
;   a0 = dsr128<6 * 2048>(kn); a1 = dsr128<6 * 2048 + 512>(kn); LGKM_W2(2, b0, b1); MM(b0, b1, qr[5]);
;   b0 = dsr128<7 * 2048>(kn); b1 = dsr128<7 * 2048 + 512>(kn); LGKM_W2(2, a0, a1); MM(a0, a1, qr[6]);
;   a0 = dsr128<0 * 2048>(kr); a1 = dsr128<0 * 2048 + 512>(kr); qa_ = dsr128<0 * 1024>(qa); LGKM_W2(3, b0, b1); MM(b0, b1, qr[7]);
;   b0 = dsr128<1 * 2048>(kr); b1 = dsr128<1 * 2048 + 512>(kr); qb_ = dsr128<1 * 1024>(qa); LGKM_W3(3, a0, a1, qa_); MM(a0, a1, qa_);
;   a0 = dsr128<2 * 2048>(kr); a1 = dsr128<2 * 2048 + 512>(kr); qa_ = dsr128<2 * 1024>(qa); LGKM_W3(3, b0, b1, qb_); MM(b0, b1, qb_);
;   b0 = dsr128<3 * 2048>(kr); b1 = dsr128<3 * 2048 + 512>(kr); qb_ = dsr128<3 * 1024>(qa); LGKM_W3(3, a0, a1, qa_); MM(a0, a1, qa_);
;   LGKM_W3(0, b0, b1, qb_); MM(b0, b1, qb_);
.LBB0_1372:
	ds_read_b128 v[98:101], v211 offset:0
	ds_read_b128 v[178:181], v211 offset:0x200
	ds_read_b128 v[192:195], v211 offset:0x800
	ds_read_b128 v[216:219], v211 offset:0xa00
	v_add_f32_e32 v0, 0, v172
	s_waitcnt lgkmcnt(2)
	v_add_f32_e32 v0, v175, v0
	v_mfma_f32_32x32x16_bf16 v[114:129], v[98:101], v[130:133], v[66:81]
	v_add_f32_e32 v0, v173, v0
	v_add_f32_e32 v0, v176, v0
	v_add_f32_e32 v0, v174, v0
	v_add_f32_e32 v0, v177, v0
	v_add_f32_e32 v0, v170, v0
	v_add_f32_e32 v0, v171, v0
	v_add_f32_e32 v0, v166, v0
	v_mfma_f32_32x32x16_bf16 v[98:113], v[178:181], v[130:133], v[66:81]
	ds_read_b128 v[178:181], v211 offset:0x1000
	ds_read_b128 v[220:223], v211 offset:0x1200
	s_waitcnt lgkmcnt(2)
	v_add_f32_e32 v0, v168, v0
	v_add_f32_e32 v0, v167, v0
	v_add_f32_e32 v0, v169, v0
	v_exp_f32_e32 v82, v82
	v_mfma_f32_32x32x16_bf16 v[114:129], v[192:195], v[134:137], v[114:129]
	ds_read_b128 v[192:195], v211 offset:0x1800
	v_add_f32_e32 v0, v162, v0
	v_exp_f32_e32 v83, v83
	v_add_f32_e32 v0, v164, v0
	v_exp_f32_e32 v84, v84
	v_add_f32_e32 v0, v163, v0
	v_exp_f32_e32 v85, v85
	v_mfma_f32_32x32x16_bf16 v[98:113], v[216:219], v[134:137], v[98:113]
	ds_read_b128 v[216:219], v211 offset:0x1a00
	s_waitcnt lgkmcnt(2)
	v_add_f32_e32 v0, v165, v0
	v_exp_f32_e32 v86, v86
	v_add_f32_e32 v0, v82, v0
	v_exp_f32_e32 v87, v87
	v_add_f32_e32 v0, v83, v0
	v_mfma_f32_32x32x16_bf16 v[114:129], v[178:181], v[138:141], v[114:129]
	ds_read_b128 v[178:181], v211 offset:0x2000
	v_exp_f32_e32 v88, v88
	v_add_f32_e32 v0, v84, v0
	v_exp_f32_e32 v89, v89
	v_add_f32_e32 v0, v85, v0
	v_add_f32_e32 v0, v86, v0
	v_add_f32_e32 v0, v87, v0
	v_mfma_f32_32x32x16_bf16 v[98:113], v[220:223], v[138:141], v[98:113]
	ds_read_b128 v[220:223], v211 offset:0x2200
	s_waitcnt lgkmcnt(2)
	v_add_f32_e32 v0, v88, v0
	v_add_f32_e32 v0, v89, v0
	v_mfma_f32_32x32x16_bf16 v[114:129], v[192:195], v[142:145], v[114:129]
	ds_read_b128 v[192:195], v211 offset:0x2800
	v_mfma_f32_32x32x16_bf16 v[98:113], v[216:219], v[142:145], v[98:113]
	ds_read_b128 v[216:219], v211 offset:0x2a00
	s_waitcnt lgkmcnt(2)
	s_nop 0
	v_mfma_f32_32x32x16_bf16 v[114:129], v[178:181], v[146:149], v[114:129]
	ds_read_b128 v[178:181], v211 offset:0x3000
	v_mfma_f32_32x32x16_bf16 v[98:113], v[220:223], v[146:149], v[98:113]
	ds_read_b128 v[220:223], v211 offset:0x3200
	s_waitcnt lgkmcnt(2)
	s_nop 0
	v_mfma_f32_32x32x16_bf16 v[114:129], v[192:195], v[150:153], v[114:129]
	ds_read_b128 v[192:195], v211 offset:0x3800
	v_mfma_f32_32x32x16_bf16 v[98:113], v[216:219], v[150:153], v[98:113]
	ds_read_b128 v[216:219], v211 offset:0x3a00
	s_waitcnt lgkmcnt(2)
	s_nop 0
	v_mfma_f32_32x32x16_bf16 v[114:129], v[178:181], v[154:157], v[114:129]
	ds_read_b128 v[178:181], v212 offset:0
	v_mfma_f32_32x32x16_bf16 v[98:113], v[220:223], v[154:157], v[98:113]
	ds_read_b128 v[220:223], v212 offset:0x200
	ds_read_b128 v[224:227], v201 offset:0
	s_waitcnt lgkmcnt(3)
	s_nop 0
	v_mfma_f32_32x32x16_bf16 v[114:129], v[192:195], v[158:161], v[114:129]
	ds_read_b128 v[192:195], v212 offset:0x800
	v_mfma_f32_32x32x16_bf16 v[98:113], v[216:219], v[158:161], v[98:113]
	ds_read_b128 v[216:219], v212 offset:0xa00
	ds_read_b128 v[228:231], v201 offset:0x400
	s_waitcnt lgkmcnt(3)
	s_nop 0
	v_mfma_f32_32x32x16_bf16 v[114:129], v[178:181], v[224:227], v[114:129]
	ds_read_b128 v[178:181], v212 offset:0x1000
	v_mfma_f32_32x32x16_bf16 v[98:113], v[220:223], v[224:227], v[98:113]
	ds_read_b128 v[220:223], v212 offset:0x1200
	ds_read_b128 v[224:227], v201 offset:0x800
	s_waitcnt lgkmcnt(3)
	s_nop 0
	v_mfma_f32_32x32x16_bf16 v[114:129], v[192:195], v[228:231], v[114:129]
	ds_read_b128 v[192:195], v212 offset:0x1800
	v_mfma_f32_32x32x16_bf16 v[98:113], v[216:219], v[228:231], v[98:113]
	ds_read_b128 v[216:219], v212 offset:0x1a00
	ds_read_b128 v[228:231], v201 offset:0xc00
	s_waitcnt lgkmcnt(3)
	s_nop 0
	s_waitcnt lgkmcnt(0)
; #define PV_WAIT(n, f) asm volatile("s_waitcnt lgkmcnt(" #n ")" : "+v"(f.l0), "+v"(f.h0), "+v"(f.l1), "+v"(f.h1), "+v"(f.l2), "+v"(f.h2), "+v"(f.l3), "+v"(f.h3) :: "memory")
; template <bool START>
; __device__ __forceinline__ void partialSM(f32x16& p0, f32x16& p1, float& mhat, f32x16& negm, float& alpha) {
;   float pmax = p0[0];
; #pragma unroll
;   for (int r = 1; r < 16; ++r) pmax = fmaxf(pmax, p0[r]);
; #pragma unroll
;   for (int r = 0; r < 16; ++r) pmax = fmaxf(pmax, p1[r]);
;   { auto rr = __builtin_amdgcn_permlane32_swap(__float_as_uint(pmax), __float_as_uint(pmax), false, false);
;     pmax = fmaxf(__uint_as_float(rr[0]), __uint_as_float(rr[1])); }
;   alpha = 1.f;
;   if (START || __builtin_expect(__any(pmax > THRL), 0)) {
; __device__ __forceinline__ void pv_d0(f32x16* o, int vb, bf16x8 pa0, bf16x8 pa1, bf16x8 pa2, bf16x8 pa3) {
;   VF fa, fb;
;   pv_rd<0>(fa, vb);
;   pv_rd<1>(fb, vb); PV_WAIT(8, fa); pv_mm(o[0], fa, pa0, pa1, pa2, pa3);
;   pv_rd<2>(fa, vb); PV_WAIT(8, fb); pv_mm(o[1], fb, pa0, pa1, pa2, pa3);
;   pv_rd<3>(fb, vb); PV_WAIT(8, fa); pv_mm(o[2], fa, pa0, pa1, pa2, pa3);
;   PV_WAIT(0, fb); pv_mm(o[3], fb, pa0, pa1, pa2, pa3);
; }
	v_mfma_f32_32x32x16_bf16 v[114:129], v[178:181], v[224:227], v[114:129]
	v_exp_f32_e32 v178, v90
	v_exp_f32_e32 v179, v91
	v_exp_f32_e32 v180, v92
	v_exp_f32_e32 v181, v93
	v_add_f32_e32 v0, v178, v0
	v_add_f32_e32 v0, v179, v0
	v_add_f32_e32 v0, v180, v0
	v_mfma_f32_32x32x16_bf16 v[98:113], v[220:223], v[224:227], v[98:113]
	v_add_f32_e32 v0, v181, v0
	v_cvt_pk_bf16_f32 v90, v172, v175
	v_cvt_pk_bf16_f32 v91, v173, v176
	v_cvt_pk_bf16_f32 v92, v174, v177
	v_cvt_pk_bf16_f32 v93, v170, v171
	s_nop 0
	v_permlane32_swap_b32_e32 v90, v92
	v_mfma_f32_32x32x16_bf16 v[114:129], v[192:195], v[228:231], v[114:129]
	v_exp_f32_e32 v192, v94
	v_exp_f32_e32 v193, v95
	v_exp_f32_e32 v194, v96
	v_exp_f32_e32 v195, v97
	v_add_f32_e32 v0, v192, v0
	v_add_f32_e32 v0, v193, v0
	v_add_f32_e32 v0, v194, v0
	v_mfma_f32_32x32x16_bf16 v[98:113], v[216:219], v[228:231], v[98:113]
	v_add_f32_e32 v0, v195, v0
	v_mov_b32_e32 v216, v0
	s_nop 1
	v_permlane32_swap_b32_e32 v0, v216
	v_cvt_pk_bf16_f32 v94, v166, v168
	v_cvt_pk_bf16_f32 v95, v167, v169
	v_cvt_pk_bf16_f32 v96, v162, v164
	v_cvt_pk_bf16_f32 v97, v163, v165
	v_cvt_pk_bf16_f32 v174, v82, v83
	v_cvt_pk_bf16_f32 v175, v84, v85
	v_cvt_pk_bf16_f32 v176, v86, v87
	v_cvt_pk_bf16_f32 v177, v88, v89
	v_cvt_pk_bf16_f32 v178, v178, v179
	v_cvt_pk_bf16_f32 v179, v180, v181
	v_cvt_pk_bf16_f32 v180, v192, v193
	v_cvt_pk_bf16_f32 v181, v194, v195
	v_permlane32_swap_b32_e32 v91, v93
	v_permlane32_swap_b32_e32 v94, v96
	v_permlane32_swap_b32_e32 v95, v97
	v_permlane32_swap_b32_e32 v174, v176
	v_permlane32_swap_b32_e32 v175, v177
	v_permlane32_swap_b32_e32 v178, v180
	v_permlane32_swap_b32_e32 v179, v181
	v_lshl_add_u64 v[196:197], s[70:71], 0, v[190:191]
	s_mov_b32 s0, 0x60e0000
	v_add_co_u32_e32 v82, vcc, s0, v196
	v_lshl_add_u64 v[194:195], s[70:71], 0, v[186:187]
	s_nop 0
	v_addc_co_u32_e32 v83, vcc, 0, v197, vcc
	s_mov_b32 s0, 0xe1c4000
	global_load_dwordx4 v[162:165], v[82:83], off
	global_load_dwordx4 v[166:169], v[82:83], off offset:128
	v_add_co_u32_e32 v82, vcc, s0, v194
	v_lshl_add_u64 v[192:193], s[70:71], 0, v[188:189]
	s_nop 0
	v_addc_co_u32_e32 v83, vcc, 0, v195, vcc
	s_mov_b32 s0, 0xa150000
	v_add_co_u32_e32 v84, vcc, s0, v192
	s_mov_b32 s0, 0xa158000
	s_nop 0
	v_addc_co_u32_e32 v85, vcc, 0, v193, vcc
	v_add_co_u32_e32 v86, vcc, s0, v192
	global_load_dwordx4 v[170:173], v[82:83], off
	s_nop 0
	global_load_dwordx4 v[82:85], v[84:85], off
	v_addc_co_u32_e32 v87, vcc, 0, v193, vcc
	global_load_dwordx4 v[86:89], v[86:87], off
	ds_read_b64_tr_b16 v[218:219], v207 offset:0
	ds_read_b64_tr_b16 v[220:221], v207 offset:0x800
	ds_read_b64_tr_b16 v[222:223], v207 offset:0x1000
	ds_read_b64_tr_b16 v[224:225], v207 offset:0x1800
	ds_read_b64_tr_b16 v[226:227], v207 offset:0x2000
	ds_read_b64_tr_b16 v[228:229], v207 offset:0x2800
	ds_read_b64_tr_b16 v[230:231], v207 offset:0x3000
	ds_read_b64_tr_b16 v[232:233], v207 offset:0x3800
	ds_read_b64_tr_b16 v[234:235], v207 offset:0x200
	ds_read_b64_tr_b16 v[236:237], v207 offset:0xa00
	ds_read_b64_tr_b16 v[238:239], v207 offset:0x1200
	ds_read_b64_tr_b16 v[240:241], v207 offset:0x1a00
	ds_read_b64_tr_b16 v[242:243], v207 offset:0x2200
	ds_read_b64_tr_b16 v[244:245], v207 offset:0x2a00
	ds_read_b64_tr_b16 v[246:247], v207 offset:0x3200
	ds_read_b64_tr_b16 v[248:249], v207 offset:0x3a00
	s_nop 0
	s_waitcnt lgkmcnt(8)
	s_nop 0
	v_mfma_f32_32x32x16_bf16 v[50:65], v[90:93], v[218:221], v[50:65]
	ds_read_b64_tr_b16 v[218:219], v207 offset:0x400
	ds_read_b64_tr_b16 v[220:221], v207 offset:0xc00
	v_mfma_f32_32x32x16_bf16 v[50:65], v[94:97], v[222:225], v[50:65]
	ds_read_b64_tr_b16 v[222:223], v207 offset:0x1400
	ds_read_b64_tr_b16 v[224:225], v207 offset:0x1c00
	v_mfma_f32_32x32x16_bf16 v[50:65], v[174:177], v[226:229], v[50:65]
	ds_read_b64_tr_b16 v[226:227], v207 offset:0x2400
	ds_read_b64_tr_b16 v[228:229], v207 offset:0x2c00
	v_mfma_f32_32x32x16_bf16 v[50:65], v[178:181], v[230:233], v[50:65]
	ds_read_b64_tr_b16 v[230:231], v207 offset:0x3400
	ds_read_b64_tr_b16 v[232:233], v207 offset:0x3c00
	s_waitcnt lgkmcnt(8)
	s_nop 0
	v_mfma_f32_32x32x16_bf16 v[34:49], v[90:93], v[234:237], v[34:49]
	ds_read_b64_tr_b16 v[234:235], v207 offset:0x600
	ds_read_b64_tr_b16 v[236:237], v207 offset:0xe00
	v_mfma_f32_32x32x16_bf16 v[34:49], v[94:97], v[238:241], v[34:49]
	ds_read_b64_tr_b16 v[238:239], v207 offset:0x1600
	ds_read_b64_tr_b16 v[240:241], v207 offset:0x1e00
	v_mfma_f32_32x32x16_bf16 v[34:49], v[174:177], v[242:245], v[34:49]
	ds_read_b64_tr_b16 v[242:243], v207 offset:0x2600
	ds_read_b64_tr_b16 v[244:245], v207 offset:0x2e00
	v_mfma_f32_32x32x16_bf16 v[34:49], v[178:181], v[246:249], v[34:49]
	ds_read_b64_tr_b16 v[246:247], v207 offset:0x3600
	ds_read_b64_tr_b16 v[248:249], v207 offset:0x3e00
	s_waitcnt lgkmcnt(8)
	s_nop 0
	s_waitcnt lgkmcnt(0)
	v_mfma_f32_32x32x16_bf16 v[18:33], v[90:93], v[218:221], v[18:33]
	v_mfma_f32_32x32x16_bf16 v[2:17], v[90:93], v[234:237], v[2:17]
	v_max_f32_e32 v90, v115, v115
	v_max_f32_e32 v91, v114, v114
	v_max_f32_e32 v90, v91, v90
	v_max3_f32 v90, v90, v116, v117
	v_max3_f32 v90, v90, v118, v119
	v_max3_f32 v90, v90, v120, v121
	v_max3_f32 v90, v90, v122, v123
	v_mfma_f32_32x32x16_bf16 v[18:33], v[94:97], v[222:225], v[18:33]
	v_max3_f32 v90, v90, v124, v125
	v_max3_f32 v90, v90, v126, v127
	v_max3_f32 v90, v90, v128, v129
	v_max3_f32 v90, v90, v98, v99
	v_max3_f32 v90, v90, v100, v101
	v_max3_f32 v90, v90, v102, v103
	v_max3_f32 v90, v90, v104, v105
	v_mfma_f32_32x32x16_bf16 v[2:17], v[94:97], v[238:241], v[2:17]
	v_max3_f32 v90, v90, v106, v107
	v_max3_f32 v90, v90, v108, v109
	v_max3_f32 v90, v90, v110, v111
	v_max3_f32 v90, v90, v112, v113
	v_mov_b32_e32 v91, v90
	s_nop 1
	v_permlane32_swap_b32_e32 v90, v91
	v_mfma_f32_32x32x16_bf16 v[18:33], v[174:177], v[226:229], v[18:33]
	v_max_f32_e32 v91, v91, v91
	v_max_f32_e32 v90, v90, v90
	v_max_f32_e32 v90, v90, v91
	v_cmp_lt_f32_e32 vcc, s75, v90
	v_mfma_f32_32x32x16_bf16 v[2:17], v[174:177], v[242:245], v[2:17]
	v_mfma_f32_32x32x16_bf16 v[18:33], v[178:181], v[230:233], v[18:33]
	v_mfma_f32_32x32x16_bf16 v[2:17], v[178:181], v[246:249], v[2:17]
	s_cbranch_vccnz .LBB0_1390
	v_mov_b32_e32 v217, 1.0
	s_branch .LBB0_1377

; __device__ __forceinline__ int crow(int r, int hi) { return (r & 3) + 8 * (r >> 2) + 4 * hi; }
; #define RESC(a) do { if (__any((a) < 1.f)) { if (hi == 0) al_l[r32] = (a); asm volatile("s_waitcnt lgkmcnt(0)" ::: "memory"); \
;     _Pragma("unroll") for (int d = 0; d < 4; ++d) _Pragma("unroll") for (int r = 0; r < 16; ++r) o[d][r] *= al_l[crow(r, hi)]; } } while (0)
; template <bool START>
; __device__ __forceinline__ void partialSM(f32x16& p0, f32x16& p1, float& mhat, f32x16& negm, float& alpha) {
;   float pmax = p0[0];
; #pragma unroll
;   for (int r = 1; r < 16; ++r) pmax = fmaxf(pmax, p0[r]);
; #pragma unroll
;   for (int r = 0; r < 16; ++r) pmax = fmaxf(pmax, p1[r]);
;   { auto rr = __builtin_amdgcn_permlane32_swap(__float_as_uint(pmax), __float_as_uint(pmax), false, false);
;     pmax = fmaxf(__uint_as_float(rr[0]), __uint_as_float(rr[1])); }
;   alpha = 1.f;
;   if (START || __builtin_expect(__any(pmax > THRL), 0)) {
; __device__ __forceinline__ void kmask(f32x16& p0, f32x16& p1, int nv, int hi) {
; #pragma unroll
;   for (int r = 0; r < 16; ++r) { const int k = crow(r, hi); if (k >= nv) p0[r] = -1e30f; if (k + 32 >= nv) p1[r] = -1e30f; }
; }
; __device__ __forceinline__ void attn_unit(const bf16* __restrict__ Qg, const bf16* __restrict__ KNg, const bf16* __restrict__ KRg, const bf16* __restrict__ Vg, bf16* __restrict__ AO, ...
;     ...
;     pv_d0(o, vb0 + SHM_V, pa0, pa1, pa2, pa3);
;     if (tbeg + j + 1 == NTt - 1) kmask(pA0, pA1, nv_last, hi);
;     partialSM<false>(pA0, pA1, mhat, negm, alA);
;     RESC(alA);
.LBB0_1379:
	v_add_co_u32_e32 v98, vcc, 0xa160000, v192
	s_nop 1
	v_addc_co_u32_e32 v99, vcc, 0, v193, vcc
	v_add_co_u32_e32 v102, vcc, 0xa168000, v192
	s_nop 1
	v_addc_co_u32_e32 v103, vcc, 0, v193, vcc
	global_load_dwordx4 v[98:101], v[98:99], off
	s_nop 0
	global_load_dwordx4 v[102:105], v[102:103], off
	ds_read_b64_tr_b16 v[192:193], v213 offset:0
	ds_read_b64_tr_b16 v[194:195], v213 offset:0x800
	ds_read_b64_tr_b16 v[220:221], v213 offset:0x1000
	ds_read_b64_tr_b16 v[222:223], v213 offset:0x1800
	ds_read_b64_tr_b16 v[224:225], v213 offset:0x2000
	ds_read_b64_tr_b16 v[226:227], v213 offset:0x2800
	ds_read_b64_tr_b16 v[228:229], v213 offset:0x3000
	ds_read_b64_tr_b16 v[230:231], v213 offset:0x3800
	ds_read_b64_tr_b16 v[232:233], v213 offset:0x200
	ds_read_b64_tr_b16 v[234:235], v213 offset:0xa00
	ds_read_b64_tr_b16 v[236:237], v213 offset:0x1200
	ds_read_b64_tr_b16 v[238:239], v213 offset:0x1a00
	ds_read_b64_tr_b16 v[240:241], v213 offset:0x2200
	ds_read_b64_tr_b16 v[242:243], v213 offset:0x2a00
	ds_read_b64_tr_b16 v[244:245], v213 offset:0x3200
	ds_read_b64_tr_b16 v[246:247], v213 offset:0x3a00
	s_nop 0
	s_waitcnt lgkmcnt(8)
	s_cmp_lg_u32 s97, s91
	v_mfma_f32_32x32x16_bf16 v[50:65], v[106:109], v[192:195], v[50:65]
	ds_read_b64_tr_b16 v[192:193], v213 offset:0x400
	ds_read_b64_tr_b16 v[194:195], v213 offset:0xc00
	v_mfma_f32_32x32x16_bf16 v[50:65], v[110:113], v[220:223], v[50:65]
	ds_read_b64_tr_b16 v[220:221], v213 offset:0x1400
	ds_read_b64_tr_b16 v[222:223], v213 offset:0x1c00
	v_mfma_f32_32x32x16_bf16 v[50:65], v[174:177], v[224:227], v[50:65]
	ds_read_b64_tr_b16 v[224:225], v213 offset:0x2400
	ds_read_b64_tr_b16 v[226:227], v213 offset:0x2c00
	v_mfma_f32_32x32x16_bf16 v[50:65], v[178:181], v[228:231], v[50:65]
	ds_read_b64_tr_b16 v[228:229], v213 offset:0x3400
	ds_read_b64_tr_b16 v[230:231], v213 offset:0x3c00
	s_waitcnt lgkmcnt(8)
	s_nop 0
	v_mfma_f32_32x32x16_bf16 v[34:49], v[106:109], v[232:235], v[34:49]
	ds_read_b64_tr_b16 v[232:233], v213 offset:0x600
	ds_read_b64_tr_b16 v[234:235], v213 offset:0xe00
	v_mfma_f32_32x32x16_bf16 v[34:49], v[110:113], v[236:239], v[34:49]
	ds_read_b64_tr_b16 v[236:237], v213 offset:0x1600
	ds_read_b64_tr_b16 v[238:239], v213 offset:0x1e00
	v_mfma_f32_32x32x16_bf16 v[34:49], v[174:177], v[240:243], v[34:49]
	ds_read_b64_tr_b16 v[240:241], v213 offset:0x2600
	ds_read_b64_tr_b16 v[242:243], v213 offset:0x2e00
	v_mfma_f32_32x32x16_bf16 v[34:49], v[178:181], v[244:247], v[34:49]
	ds_read_b64_tr_b16 v[244:245], v213 offset:0x3600
	ds_read_b64_tr_b16 v[246:247], v213 offset:0x3e00
	s_waitcnt lgkmcnt(8)
	s_nop 0
	s_waitcnt lgkmcnt(0)
	v_mfma_f32_32x32x16_bf16 v[18:33], v[106:109], v[192:195], v[18:33]
	v_mfma_f32_32x32x16_bf16 v[2:17], v[106:109], v[232:235], v[2:17]
	v_max_f32_e32 v106, v115, v115
	v_max_f32_e32 v107, v114, v114
	v_max_f32_e32 v106, v107, v106
	v_max3_f32 v106, v106, v116, v117
	v_max3_f32 v106, v106, v118, v119
	v_mfma_f32_32x32x16_bf16 v[18:33], v[110:113], v[220:223], v[18:33]
	v_max3_f32 v106, v106, v120, v121
	v_max3_f32 v106, v106, v122, v123
	v_max3_f32 v106, v106, v124, v125
	v_max3_f32 v106, v106, v126, v127
	v_max3_f32 v106, v106, v128, v129
	v_mfma_f32_32x32x16_bf16 v[2:17], v[110:113], v[236:239], v[2:17]
	v_max3_f32 v106, v106, v82, v83
	v_max3_f32 v106, v106, v84, v85
	v_max3_f32 v106, v106, v86, v87
	v_max3_f32 v106, v106, v88, v89
	v_max3_f32 v106, v106, v90, v91
	v_mfma_f32_32x32x16_bf16 v[18:33], v[174:177], v[224:227], v[18:33]
	v_max3_f32 v106, v106, v92, v93
	v_max3_f32 v106, v106, v94, v95
	v_max3_f32 v106, v106, v96, v97
	v_mfma_f32_32x32x16_bf16 v[2:17], v[174:177], v[240:243], v[2:17]
	v_mov_b32_e32 v107, v106
	s_nop 1
	v_permlane32_swap_b32_e32 v106, v107
	v_mfma_f32_32x32x16_bf16 v[18:33], v[178:181], v[228:231], v[18:33]
	v_max_f32_e32 v107, v107, v107
	v_max_f32_e32 v106, v106, v106
	v_max_f32_e32 v107, v106, v107
	v_cmp_lt_f32_e32 vcc, s75, v107
	v_mov_b32_e32 v106, 1.0
	v_mfma_f32_32x32x16_bf16 v[2:17], v[178:181], v[244:247], v[2:17]
	s_cbranch_scc1 .LBB0_1381
	v_cndmask_b32_e64 v129, v198, v129, s[4:5]
	v_cndmask_b32_e64 v128, v198, v128, s[8:9]
	v_cndmask_b32_e64 v127, v198, v127, s[10:11]
	v_cndmask_b32_e64 v126, v198, v126, s[12:13]
	v_cndmask_b32_e64 v125, v198, v125, s[14:15]
	v_cndmask_b32_e64 v124, v198, v124, s[16:17]
	v_cndmask_b32_e64 v123, v198, v123, s[18:19]
	v_cndmask_b32_e64 v122, v198, v122, s[20:21]
	v_cndmask_b32_e64 v121, v198, v121, s[22:23]
	v_cndmask_b32_e64 v120, v198, v120, s[24:25]
	v_cndmask_b32_e64 v119, v198, v119, s[26:27]
	v_cndmask_b32_e64 v118, v198, v118, s[28:29]
	v_cndmask_b32_e64 v117, v198, v117, s[30:31]
	v_cndmask_b32_e64 v116, v198, v116, s[34:35]
	v_cndmask_b32_e64 v115, v198, v115, s[36:37]
	v_cndmask_b32_e64 v114, v198, v114, s[38:39]
	v_cndmask_b32_e64 v97, v198, v97, s[6:7]
	v_cndmask_b32_e64 v96, v198, v96, s[40:41]
	v_cndmask_b32_e64 v95, v198, v95, s[42:43]
	v_cndmask_b32_e64 v94, v198, v94, s[44:45]
	v_cndmask_b32_e64 v93, v198, v93, s[46:47]
	v_cndmask_b32_e64 v92, v198, v92, s[48:49]
	v_cndmask_b32_e64 v91, v198, v91, s[50:51]
	v_cndmask_b32_e64 v90, v198, v90, s[52:53]
	v_cndmask_b32_e64 v89, v198, v89, s[54:55]
	v_cndmask_b32_e64 v88, v198, v88, s[56:57]
	v_cndmask_b32_e64 v87, v198, v87, s[58:59]
	v_cndmask_b32_e64 v86, v198, v86, s[60:61]
	v_cndmask_b32_e64 v85, v198, v85, s[62:63]
	v_cndmask_b32_e64 v84, v198, v84, s[64:65]
	v_cndmask_b32_e64 v83, v198, v83, s[66:67]
	v_cndmask_b32_e64 v82, v198, v82, s[68:69]
	v_max_f32_e32 v106, v115, v115
	v_max_f32_e32 v107, v114, v114
	v_max_f32_e32 v106, v107, v106
	v_max3_f32 v106, v106, v116, v117
	v_max3_f32 v106, v106, v118, v119
	v_max3_f32 v106, v106, v120, v121
	v_max3_f32 v106, v106, v122, v123
	v_max3_f32 v106, v106, v124, v125
	v_max3_f32 v106, v106, v126, v127
	v_max3_f32 v106, v106, v128, v129
	v_max3_f32 v106, v106, v82, v83
	v_max3_f32 v106, v106, v84, v85
	v_max3_f32 v106, v106, v86, v87
	v_max3_f32 v106, v106, v88, v89
	v_max3_f32 v106, v106, v90, v91
	v_max3_f32 v106, v106, v92, v93
	v_max3_f32 v106, v106, v94, v95
	v_max3_f32 v106, v106, v96, v97
	v_mov_b32_e32 v107, v106
	s_nop 1
	v_permlane32_swap_b32_e32 v106, v107
	v_max_f32_e32 v107, v107, v107
	v_max_f32_e32 v106, v106, v106
	v_max_f32_e32 v107, v106, v107
	v_cmp_lt_f32_e32 vcc, s75, v107
	v_mov_b32_e32 v106, 1.0

; #define KWRITE(b) do { *(bf16x8*)(KN_lds + (b) * SHM_KN + kwoff) = ks0; *(bf16x8*)(KN_lds + (b) * SHM_KN + 8192 + kwoff) = ks1; *(bf16x8*)(KR_lds + (b) * SHM_KR + kwoff) = kr0; } while (0)
; #define VWRITE(b) do { *(bf16x8*)(V_lds + (b) * SHM_V + vst0) = vs0; *(bf16x8*)(V_lds + (b) * SHM_V + vst1) = vs1; } while (0)
; #define SWAIT() asm volatile("s_waitcnt vmcnt(0)" ::: "memory")
; template <bool START>
; __device__ __forceinline__ void partialSM(f32x16& p0, f32x16& p1, float& mhat, f32x16& negm, float& alpha) {
;     ...
;   for (int r = 0; r < 16; ++r) p0[r] = __builtin_amdgcn_exp2f(p0[r]);
; }
; __device__ __forceinline__ void finishSM(f32x16& p0, f32x16& p1, float alpha, float& l_reg, bf16x8& pa0, bf16x8& pa1, bf16x8& pa2, bf16x8& pa3) {
; #pragma unroll
;   for (int r = 0; r < 16; ++r) p1[r] = __builtin_amdgcn_exp2f(p1[r]);
;   float ps = 0;
; #pragma unroll
;   for (int r = 0; r < 16; ++r) ps += p0[r];
; #pragma unroll
;   for (int r = 0; r < 16; ++r) ps += p1[r];
;   { auto rr = __builtin_amdgcn_permlane32_swap(__float_as_uint(ps), __float_as_uint(ps), false, false);
;     ps = __uint_as_float(rr[0]) + __uint_as_float(rr[1]); }
;   l_reg = l_reg * alpha + ps;
; __device__ __forceinline__ void attn_unit(const bf16* __restrict__ Qg, const bf16* __restrict__ KNg, const bf16* __restrict__ KRg, const bf16* __restrict__ Vg, bf16* __restrict__ AO, ...
;     ...
;     SWAIT(); if (more) KWRITE(1); VWRITE(0); __syncthreads();
;   }
.LBB0_1388:
	s_waitcnt vmcnt(0)
	ds_write_b128 v203, v[98:101]
	ds_write_b128 v204, v[102:105]
	v_exp_f32_e32 v172, v114
	v_exp_f32_e32 v175, v115
	v_exp_f32_e32 v173, v116
	v_exp_f32_e32 v176, v117
	v_exp_f32_e32 v174, v118
	v_exp_f32_e32 v177, v119
	v_exp_f32_e32 v170, v120
	v_exp_f32_e32 v171, v121
	v_exp_f32_e32 v166, v122
	v_exp_f32_e32 v168, v123
	v_exp_f32_e32 v167, v124
	v_exp_f32_e32 v169, v125
	v_exp_f32_e32 v162, v126
	v_exp_f32_e32 v164, v127
	v_exp_f32_e32 v163, v128
	v_exp_f32_e32 v165, v129
	v_add_f32_e32 v0, v0, v216
	v_fmac_f32_e32 v0, v215, v214
	v_add_f32_e32 v214, v218, v219
	s_add_i32 s0, s91, 2
	v_fmac_f32_e32 v214, v0, v217
	v_lshl_add_u64 v[186:187], v[186:187], 0, s[80:81]
	v_lshl_add_u64 v[188:189], v[188:189], 0, s[82:83]
	s_cmp_ge_u32 s91, s90
	v_lshl_add_u64 v[190:191], v[190:191], 0, s[82:83]
	s_mov_b32 s91, s0
	v_mov_b32_e32 v215, v106
	s_waitcnt lgkmcnt(0)
	s_barrier
	s_cbranch_scc0 .LBB0_1372
	s_branch .LBB0_1392
